# P0: waves 4-7 of each block run weight transposes before the rmsnorm rows (role skew so latency-bound and bandwidth-bound segments overlap)
# speedup vs baseline: 1.0015x; 1.0015x over previous
.LBB0_17:
	v_writelane_b32 v236, s36, 7
	s_nop 1
	v_writelane_b32 v236, s37, 8
	v_writelane_b32 v236, s38, 9
	v_writelane_b32 v236, s39, 10
	v_writelane_b32 v236, s40, 11
	v_writelane_b32 v236, s41, 12
	v_writelane_b32 v236, s42, 13
	v_writelane_b32 v236, s43, 14
	v_writelane_b32 v236, s44, 15
	v_writelane_b32 v236, s45, 16
	v_writelane_b32 v236, s46, 17
	v_writelane_b32 v236, s47, 18
	v_writelane_b32 v236, s48, 19
	v_writelane_b32 v236, s49, 20
	v_writelane_b32 v236, s50, 21
	v_writelane_b32 v236, s51, 22
	s_load_dwordx16 s[36:51], s[0:1], 0x40
	s_waitcnt lgkmcnt(0)
	v_writelane_b32 v236, s36, 23
	s_nop 1
	v_writelane_b32 v236, s37, 24
	v_writelane_b32 v236, s38, 25
	v_writelane_b32 v236, s39, 26
	v_writelane_b32 v236, s40, 27
	v_writelane_b32 v236, s41, 28
	v_writelane_b32 v236, s42, 29
	v_writelane_b32 v236, s43, 30
	v_writelane_b32 v236, s44, 31
	v_writelane_b32 v236, s45, 32
	v_writelane_b32 v236, s46, 33
	v_writelane_b32 v236, s47, 34
	v_writelane_b32 v236, s48, 35
	v_writelane_b32 v236, s49, 36
	v_writelane_b32 v236, s50, 37
	v_writelane_b32 v236, s51, 38
	s_load_dwordx16 s[36:51], s[0:1], 0x80
	s_lshl_b32 s0, s30, 3
	s_waitcnt lgkmcnt(0)
	v_writelane_b32 v236, s36, 39
	s_nop 1
	v_writelane_b32 v236, s37, 40
	v_writelane_b32 v236, s38, 41
	v_writelane_b32 v236, s39, 42
	v_writelane_b32 v236, s40, 43
	v_writelane_b32 v236, s41, 44
	v_writelane_b32 v236, s42, 45
	v_writelane_b32 v236, s43, 46
	v_writelane_b32 v236, s44, 47
	v_writelane_b32 v236, s45, 48
	v_writelane_b32 v236, s46, 49
	v_writelane_b32 v236, s47, 50
	v_writelane_b32 v236, s48, 51
	v_writelane_b32 v236, s49, 52
	v_writelane_b32 v236, s50, 53
	v_writelane_b32 v236, s51, 54
	v_writelane_b32 v236, s0, 55
	s_nop 1
	v_writelane_b32 v236, s1, 56
	s_nop 0
	v_readlane_b32 s4, v236, 5
	s_cmp_lt_i32 s4, 1
	s_cselect_b64 s[0:1], -1, 0
	v_readlane_b32 s5, v236, 6
	v_writelane_b32 v236, s0, 57
	s_cmp_gt_i32 s4, 0
	s_nop 0
	v_writelane_b32 v236, s1, 58
	s_cselect_b64 s[0:1], -1, 0
	s_cmp_lt_i32 s5, 1
	s_cselect_b64 s[4:5], -1, 0
	s_or_b64 s[0:1], s[4:5], s[0:1]
	s_and_b64 vcc, exec, s[0:1]
	s_cbranch_vccnz .LBB0_205
	v_mov_b32_e32 v56, v191
	s_nop 0
	v_readfirstlane_b32 s0, v56
	s_ashr_i32 s29, s0, 6
	s_lshl_b32 s0, s2, 3
	s_add_i32 s3, s29, s0
	s_cmpk_gt_i32 s3, 0x3fff
	v_and_b32_e32 v57, 63, v56
	s_cbranch_scc1 .LBB0_21
	s_bitcmp1_b32 s3, 2
	s_cbranch_scc1 .LBB0_21
.Lp0_rows:
	v_mbcnt_lo_u32_b32 v0, -1, 0
	v_mbcnt_hi_u32_b32 v0, -1, v0
	v_and_b32_e32 v1, 64, v0
	v_add_u32_e32 v1, 64, v1
	v_xor_b32_e32 v2, 1, v0
	v_cmp_lt_i32_e32 vcc, v2, v1
	s_lshl_b32 s4, s3, 1
	s_ashr_i32 s5, s4, 31
	v_cndmask_b32_e32 v2, v0, v2, vcc
	v_lshlrev_b32_e32 v37, 2, v2
	v_xor_b32_e32 v2, 2, v0
	v_cmp_lt_i32_e32 vcc, v2, v1
	s_lshl_b32 s6, s30, 4
	s_lshl_b64 s[0:1], s[4:5], 11
	v_cndmask_b32_e32 v2, v0, v2, vcc
	v_lshlrev_b32_e32 v38, 2, v2
	v_xor_b32_e32 v2, 4, v0
	v_cmp_lt_i32_e32 vcc, v2, v1
	s_add_u32 s0, s26, s0
	s_addc_u32 s1, s27, s1
	v_cndmask_b32_e32 v2, v0, v2, vcc
	v_lshlrev_b32_e32 v39, 2, v2
	v_xor_b32_e32 v2, 8, v0
	v_cmp_lt_i32_e32 vcc, v2, v1
	s_ashr_i32 s7, s6, 31
	s_lshl_b64 s[8:9], s[6:7], 11
	v_cndmask_b32_e32 v2, v0, v2, vcc
	v_lshlrev_b32_e32 v40, 2, v2
	v_xor_b32_e32 v2, 16, v0
	v_cmp_lt_i32_e32 vcc, v2, v1
	v_readlane_b32 s36, v236, 7
	v_readlane_b32 s37, v236, 8
	v_cndmask_b32_e32 v2, v0, v2, vcc
	v_lshlrev_b32_e32 v41, 2, v2
	v_xor_b32_e32 v2, 32, v0
	v_cmp_lt_i32_e32 vcc, v2, v1
	v_mov_b32_e32 v1, 0
	s_mov_b32 s28, 0x3a800000
	v_cndmask_b32_e32 v0, v0, v2, vcc
	v_lshlrev_b32_e32 v42, 2, v0
	v_lshlrev_b32_e32 v0, 3, v57
	v_lshl_add_u64 v[2:3], s[0:1], 0, v[0:1]
	s_mov_b64 s[0:1], 0x3000e00
	v_lshl_add_u64 v[32:33], v[2:3], 0, s[0:1]
	s_lshl_b64 s[0:1], s[4:5], 12
	s_add_u32 s0, s36, s0
	v_lshlrev_b32_e32 v0, 4, v57
	s_addc_u32 s1, s37, s1
	v_lshl_add_u64 v[0:1], s[0:1], 0, v[0:1]
	s_mov_b64 s[0:1], 0x1000
	v_lshl_add_u64 v[34:35], v[0:1], 0, s[0:1]
	s_lshl_b64 s[10:11], s[6:7], 12
	v_mov_b32_e32 v36, 0x358637bd
	s_mov_b32 s5, 0x800000
	v_readlane_b32 s38, v236, 9
	v_readlane_b32 s39, v236, 10
	v_readlane_b32 s40, v236, 11
	v_readlane_b32 s41, v236, 12
	v_readlane_b32 s42, v236, 13
	v_readlane_b32 s43, v236, 14
	v_readlane_b32 s44, v236, 15
	v_readlane_b32 s45, v236, 16
	v_readlane_b32 s46, v236, 17
	v_readlane_b32 s47, v236, 18
	v_readlane_b32 s48, v236, 19
	v_readlane_b32 s49, v236, 20
	v_readlane_b32 s50, v236, 21
	v_readlane_b32 s51, v236, 22
.LBB0_20:
	global_load_dwordx4 v[16:19], v[34:35], off offset:-4096 nt
	global_load_dwordx4 v[12:15], v[34:35], off offset:-3072 nt
	global_load_dwordx4 v[4:7], v[34:35], off nt
	global_load_dwordx4 v[0:3], v[34:35], off offset:1024 nt
	global_load_dwordx4 v[20:23], v[34:35], off offset:-1024 nt
	global_load_dwordx4 v[24:27], v[34:35], off offset:-2048 nt
	global_load_dwordx4 v[8:11], v[34:35], off offset:3072 nt
	global_load_dwordx4 v[28:31], v[34:35], off offset:2048 nt
	s_add_i32 s4, s4, s6
	v_lshl_add_u64 v[34:35], v[34:35], 0, s[10:11]
	s_cmpk_gt_i32 s4, 0x7fff
	s_waitcnt vmcnt(7)
	v_pk_mul_f32 v[44:45], v[18:19], v[18:19]
	v_pk_mul_f32 v[46:47], v[16:17], v[16:17]
	s_waitcnt vmcnt(6)
	v_pk_mul_f32 v[48:49], v[14:15], v[14:15]
	v_pk_mul_f32 v[50:51], v[12:13], v[12:13]
	s_waitcnt vmcnt(5)
	v_pk_mul_f32 v[52:53], v[6:7], v[6:7]
	v_pk_mul_f32 v[54:55], v[4:5], v[4:5]
	s_waitcnt vmcnt(4)
	v_pk_mul_f32 v[58:59], v[2:3], v[2:3]
	v_pk_mul_f32 v[60:61], v[0:1], v[0:1]
	v_pk_mov_b32 v[70:71], v[46:47], v[44:45] op_sel:[1,0]
	v_mov_b32_e32 v47, v45
	v_pk_mov_b32 v[44:45], v[50:51], v[48:49] op_sel:[1,0]
	v_mov_b32_e32 v51, v49
	v_pk_mov_b32 v[48:49], v[54:55], v[52:53] op_sel:[1,0]
	v_mov_b32_e32 v55, v53
	v_pk_mov_b32 v[52:53], v[60:61], v[58:59] op_sel:[1,0]
	v_mov_b32_e32 v61, v59
	s_waitcnt vmcnt(3)
	v_mul_f32_e32 v69, v22, v22
	s_waitcnt vmcnt(2)
	v_mul_f32_e32 v62, v25, v25
	v_mul_f32_e32 v64, v27, v27
	s_waitcnt vmcnt(0)
	v_mul_f32_e32 v66, v29, v29
	v_mul_f32_e32 v68, v31, v31
	v_pk_add_f32 v[46:47], v[70:71], v[46:47]
	v_pk_add_f32 v[44:45], v[44:45], v[50:51]
	v_pk_add_f32 v[48:49], v[48:49], v[54:55]
	v_pk_add_f32 v[50:51], v[52:53], v[60:61]
	v_mul_f32_e32 v43, v20, v20
	v_mul_f32_e32 v72, v23, v23
	v_mul_f32_e32 v73, v10, v10
	v_mul_f32_e32 v74, v11, v11
	v_mul_f32_e32 v75, v21, v21
	v_mul_f32_e32 v76, v8, v8
	v_mul_f32_e32 v77, v9, v9
	v_pk_fma_f32 v[58:59], v[24:25], v[24:25], v[62:63] op_sel_hi:[1,1,0]
	v_pk_fma_f32 v[62:63], v[26:27], v[26:27], v[64:65] op_sel_hi:[1,1,0]
	v_pk_fma_f32 v[64:65], v[28:29], v[28:29], v[66:67] op_sel_hi:[1,1,0]
	v_pk_fma_f32 v[66:67], v[30:31], v[30:31], v[68:69] op_sel_hi:[1,1,0]
	v_pk_add_f32 v[46:47], v[46:47], v[46:47] op_sel:[0,1] op_sel_hi:[1,0]
	v_pk_add_f32 v[44:45], v[44:45], v[44:45] op_sel:[0,1] op_sel_hi:[1,0]
	v_pk_add_f32 v[48:49], v[48:49], v[48:49] op_sel:[0,1] op_sel_hi:[1,0]
	v_pk_add_f32 v[50:51], v[50:51], v[50:51] op_sel:[0,1] op_sel_hi:[1,0]
	v_mov_b32_e32 v59, v69
	v_mov_b32_e32 v63, v72
	v_mov_b32_e32 v65, v73
	v_mov_b32_e32 v67, v74
	v_mov_b32_e32 v47, v43
	v_mov_b32_e32 v45, v75
	v_mov_b32_e32 v49, v76
	v_mov_b32_e32 v51, v77
	v_pk_add_f32 v[52:53], v[58:59], v[62:63]
	v_pk_add_f32 v[54:55], v[64:65], v[66:67]
	v_pk_add_f32 v[44:45], v[46:47], v[44:45]
	v_pk_add_f32 v[46:47], v[48:49], v[50:51]
	v_pk_add_f32 v[44:45], v[44:45], v[52:53]
	v_pk_add_f32 v[46:47], v[46:47], v[54:55]
	v_mov_b32_e32 v49, v44
	v_mov_b32_e32 v48, v46
	v_mov_b32_e32 v44, v47
	v_pk_add_f32 v[44:45], v[48:49], v[44:45]
	ds_bpermute_b32 v47, v37, v45
	ds_bpermute_b32 v46, v37, v44
	s_waitcnt lgkmcnt(0)
	v_pk_add_f32 v[44:45], v[44:45], v[46:47]
	ds_bpermute_b32 v47, v38, v45
	ds_bpermute_b32 v46, v38, v44
	s_waitcnt lgkmcnt(0)
	v_pk_add_f32 v[44:45], v[44:45], v[46:47]
	ds_bpermute_b32 v47, v39, v45
	ds_bpermute_b32 v46, v39, v44
	s_waitcnt lgkmcnt(0)
	v_pk_add_f32 v[44:45], v[44:45], v[46:47]
	ds_bpermute_b32 v47, v40, v45
	ds_bpermute_b32 v46, v40, v44
	s_waitcnt lgkmcnt(0)
	v_pk_add_f32 v[44:45], v[44:45], v[46:47]
	ds_bpermute_b32 v47, v41, v45
	ds_bpermute_b32 v46, v41, v44
	s_waitcnt lgkmcnt(0)
	v_pk_add_f32 v[44:45], v[44:45], v[46:47]
	ds_bpermute_b32 v47, v42, v45
	ds_bpermute_b32 v46, v42, v44
	s_waitcnt lgkmcnt(0)
	v_pk_add_f32 v[44:45], v[44:45], v[46:47]
	s_nop 0
	v_pk_fma_f32 v[44:45], v[44:45], s[28:29], v[36:37] op_sel_hi:[1,0,0]
	s_nop 0
	v_mul_f32_e32 v43, 0x4b800000, v45
	v_cmp_gt_f32_e64 s[0:1], s5, v45
	v_mul_f32_e32 v46, 0x4b800000, v44
	v_cmp_gt_f32_e32 vcc, s5, v44
	v_cndmask_b32_e64 v43, v45, v43, s[0:1]
	v_rsq_f32_e32 v43, v43
	v_cndmask_b32_e32 v44, v44, v46, vcc
	v_rsq_f32_e32 v45, v44
	v_mul_f32_e32 v44, 0x45800000, v43
	v_cndmask_b32_e64 v44, v43, v44, s[0:1]
	v_mul_f32_e32 v46, 0x45800000, v45
	v_cndmask_b32_e32 v46, v45, v46, vcc
	v_pk_mul_f32 v[16:17], v[16:17], v[44:45] op_sel_hi:[1,0]
	v_pk_mul_f32 v[18:19], v[18:19], v[44:45] op_sel_hi:[1,0]
	v_pk_mul_f32 v[12:13], v[12:13], v[44:45] op_sel_hi:[1,0]
	v_pk_mul_f32 v[14:15], v[14:15], v[44:45] op_sel_hi:[1,0]
	v_pk_mul_f32 v[24:25], v[24:25], v[44:45] op_sel_hi:[1,0]
	v_pk_mul_f32 v[26:27], v[26:27], v[44:45] op_sel_hi:[1,0]
	v_pk_mul_f32 v[20:21], v[20:21], v[44:45] op_sel_hi:[1,0]
	v_pk_mul_f32 v[22:23], v[22:23], v[44:45] op_sel_hi:[1,0]
	v_pk_mul_f32 v[4:5], v[4:5], v[46:47] op_sel_hi:[1,0]
	v_pk_mul_f32 v[6:7], v[6:7], v[46:47] op_sel_hi:[1,0]
	v_pk_mul_f32 v[0:1], v[0:1], v[46:47] op_sel_hi:[1,0]
	v_pk_mul_f32 v[2:3], v[2:3], v[46:47] op_sel_hi:[1,0]
	v_pk_mul_f32 v[28:29], v[28:29], v[46:47] op_sel_hi:[1,0]
	v_pk_mul_f32 v[30:31], v[30:31], v[46:47] op_sel_hi:[1,0]
	v_pk_mul_f32 v[8:9], v[8:9], v[46:47] op_sel_hi:[1,0]
	v_pk_mul_f32 v[10:11], v[10:11], v[46:47] op_sel_hi:[1,0]
	v_cvt_pk_bf16_f32 v16, v16, v17
	v_cvt_pk_bf16_f32 v17, v18, v19
	v_cvt_pk_bf16_f32 v12, v12, v13
	v_cvt_pk_bf16_f32 v13, v14, v15
	v_cvt_pk_bf16_f32 v14, v24, v25
	v_cvt_pk_bf16_f32 v15, v26, v27
	v_cvt_pk_bf16_f32 v18, v20, v21
	v_cvt_pk_bf16_f32 v19, v22, v23
	v_cvt_pk_bf16_f32 v4, v4, v5
	v_cvt_pk_bf16_f32 v5, v6, v7
	v_cvt_pk_bf16_f32 v0, v0, v1
	v_cvt_pk_bf16_f32 v1, v2, v3
	v_cvt_pk_bf16_f32 v2, v28, v29
	v_cvt_pk_bf16_f32 v3, v30, v31
	v_cvt_pk_bf16_f32 v6, v8, v9
	v_cvt_pk_bf16_f32 v7, v10, v11
	global_store_dwordx2 v[32:33], v[16:17], off offset:-3584
	global_store_dwordx2 v[32:33], v[12:13], off offset:-3072
	global_store_dwordx2 v[32:33], v[14:15], off offset:-2560
	global_store_dwordx2 v[32:33], v[18:19], off offset:-2048
	global_store_dwordx2 v[32:33], v[4:5], off offset:-1536
	global_store_dwordx2 v[32:33], v[0:1], off offset:-1024
	global_store_dwordx2 v[32:33], v[2:3], off offset:-512
	global_store_dwordx2 v[32:33], v[6:7], off
	v_lshl_add_u64 v[32:33], v[32:33], 0, s[8:9]
	s_cbranch_scc0 .LBB0_20
	s_bitcmp1_b32 s3, 2
	s_cbranch_scc1 .LBB0_188

.Lp0_wdone:
	s_bitcmp1_b32 s3, 2
	s_cbranch_scc0 .LBB0_188
	s_cmpk_gt_i32 s3, 0x3fff
	s_cbranch_scc0 .Lp0_rows
